# norm phase: all 16 row loads (x, gamma, shift, scale) issued up front into fresh VGPRs with counted vmcnt, same fp op order
# speedup vs baseline: 1.0209x; 1.0081x over previous
; __device__ __forceinline__ unsigned pack2(float a, float b) { unsigned r; asm("s_nop 1\n\tv_cvt_pk_bf16_f32 %0, %1, %2" : "=v"(r) : "v"(a), "v"(b)); return r; }
; __device__ __forceinline__ float* wsMOD(const Params& p) { return (float*)(p.ws + OFF_MOD); }
; __device__ __forceinline__ void norm_phase(const Params& p, int layer, int which, int first) {
;     ...
;   for (int row = blockIdx.x * 8 + wave; row < TALL; row += gridDim.x * 8) {
;     int b = row / SALL; int pp = row - b * SALL; bool ctx = pp < NCTX;
;     float* xr = xrow_ptr(p, row);
;     const float* src = first ? (ctx ? p.in[2] + (size_t)(b * NCTX + pp) * DM : p.in[0] + (size_t)(b * 8192 + pp - NCTX) * DM) : xr;
;     float4 v[4]; float ss = 0;
; #pragma unroll
;     for (int i = 0; i < 4; ++i) { v[i] = *(const float4*)(src + lane * 4 + i * 256); ss += v[i].x * v[i].x + v[i].y * v[i].y + v[i].z * v[i].z + v[i].w * v[i].w; }
;     ss = wave_sum(ss);
;     float rstd = rsqrtf(ss * (1.f / 1024.f) + 1e-6f);
;     const float* mod = wsMOD(p) + (size_t)(layer * 9 + (ctx ? 8 : b)) * 6144 + (which ? 3 : 0) * 1024;
; #pragma unroll
;     for (int i = 0; i < 4; ++i) {
;       int col = lane * 4 + i * 256;
;       float4 gg = *(const float4*)(g + col), sh = *(const float4*)(mod + col), sc = *(const float4*)(mod + 1024 + col);
;       float h0 = v[i].x * rstd * gg.x * (1.f + sc.x) + sh.x, h1 = v[i].y * rstd * gg.y * (1.f + sc.y) + sh.y;
;       float h2 = v[i].z * rstd * gg.z * (1.f + sc.z) + sh.z, h3 = v[i].w * rstd * gg.w * (1.f + sc.w) + sh.w;
;       uint2 pk; pk.x = pack2(h0, h1); pk.y = pack2(h2, h3);
;       *(uint2*)(H + (size_t)row * DM + col) = pk;
;       if (first && ctx) *(float4*)(xr + col) = v[i];
;     }
;   }
.LBB0_1008:
	v_lshlrev_b32_e32 v160, 2, v22
	v_lshl_add_u64 v[0:1], v[0:1], 0, v[160:161]
	global_load_dwordx4 v[12:15], v[0:1], off
	global_load_dwordx4 v[8:11], v[0:1], off offset:1024
	global_load_dwordx4 v[4:7], v[0:1], off offset:2048
	s_nop 0
	global_load_dwordx4 v[0:3], v[0:1], off offset:3072
	global_load_dwordx4 v[48:51], v[24:25], off
	s_mov_b32 s7, 0x800000
	v_cndmask_b32_e64 v16, v16, 8, s[40:41]
	v_add_u32_e32 v16, s2, v16
	s_mov_b64 s[36:37], 0x1000
	v_mul_hi_i32_i24_e32 v17, 0x6000, v16
	v_mul_i32_i24_e32 v16, 0x6000, v16
	v_lshl_add_u64 v[16:17], s[30:31], 0, v[16:17]
	v_lshl_add_u64 v[36:37], v[16:17], 0, s[36:37]
	v_lshl_add_u64 v[38:39], v[16:17], 0, v[160:161]
	v_lshl_add_u64 v[106:107], v[36:37], 0, v[160:161]
	global_load_dwordx4 v[60:63], v[38:39], off
	v_mov_b32_e32 v29, v161
	global_load_dwordx4 v[52:55], v[106:107], off
	v_lshl_add_u64 v[100:101], v[36:37], 0, v[28:29]
	global_load_dwordx4 v[64:67], v[24:25], off offset:1024
	v_mov_b32_e32 v31, v161
	global_load_dwordx4 v[68:71], v[100:101], off
	v_lshl_add_u64 v[102:103], v[36:37], 0, v[30:31]
	global_load_dwordx4 v[72:75], v[38:39], off offset:1024
	v_mov_b32_e32 v33, v161
	global_load_dwordx4 v[76:79], v[24:25], off offset:2048
	v_lshl_add_u64 v[104:105], v[36:37], 0, v[32:33]
	global_load_dwordx4 v[80:83], v[38:39], off offset:2048
	global_load_dwordx4 v[84:87], v[102:103], off
	global_load_dwordx4 v[88:91], v[24:25], off offset:3072
	global_load_dwordx4 v[92:95], v[38:39], off offset:3072
	global_load_dwordx4 v[96:99], v[104:105], off
	v_ashrrev_i32_e32 v21, 31, v20
	v_lshlrev_b64 v[40:41], 11, v[20:21]
	s_and_b64 s[36:37], s[26:27], s[40:41]
	s_waitcnt vmcnt(15)
	v_mov_b32_e32 v56, v13
	s_waitcnt vmcnt(14)
	v_mov_b32_e32 v57, v9
	v_mov_b32_e32 v58, v12
	v_mov_b32_e32 v59, v8
	v_pk_mul_f32 v[56:57], v[56:57], v[56:57]
	s_nop 0
	v_pk_fma_f32 v[58:59], v[58:59], v[58:59], v[56:57]
	v_mov_b32_e32 v56, v14
	v_mov_b32_e32 v57, v10
	v_pk_fma_f32 v[58:59], v[56:57], v[56:57], v[58:59]
	v_mov_b32_e32 v56, v15
	v_mov_b32_e32 v57, v11
	v_pk_fma_f32 v[18:19], v[56:57], v[56:57], v[58:59]
	s_waitcnt vmcnt(13)
	v_mov_b32_e32 v56, v5
	s_waitcnt vmcnt(12)
	v_mov_b32_e32 v57, v1
	v_add_f32_e32 v17, v18, v19
	v_mov_b32_e32 v58, v4
	v_mov_b32_e32 v59, v0
	v_pk_mul_f32 v[56:57], v[56:57], v[56:57]
	s_nop 0
	v_pk_fma_f32 v[58:59], v[58:59], v[58:59], v[56:57]
	v_mov_b32_e32 v56, v6
	v_mov_b32_e32 v57, v2
	v_pk_fma_f32 v[58:59], v[56:57], v[56:57], v[58:59]
	v_mov_b32_e32 v56, v7
	v_mov_b32_e32 v57, v3
	v_pk_fma_f32 v[58:59], v[56:57], v[56:57], v[58:59]
	s_nop 0
	v_add_f32_e32 v17, v17, v58
	v_add_f32_e32 v17, v17, v59
	ds_bpermute_b32 v18, v23, v17
	s_waitcnt lgkmcnt(0)
	v_add_f32_e32 v17, v17, v18
	ds_bpermute_b32 v18, v42, v17
	s_waitcnt lgkmcnt(0)
	v_add_f32_e32 v17, v17, v18
	ds_bpermute_b32 v18, v43, v17
	s_waitcnt lgkmcnt(0)
	v_add_f32_e32 v17, v17, v18
	ds_bpermute_b32 v18, v44, v17
	s_waitcnt lgkmcnt(0)
	v_add_f32_e32 v17, v17, v18
	ds_bpermute_b32 v18, v45, v17
	s_waitcnt lgkmcnt(0)
	v_add_f32_e32 v17, v17, v18
	ds_bpermute_b32 v18, v46, v17
	s_waitcnt lgkmcnt(0)
	v_add_f32_e32 v17, v17, v18
	v_fmamk_f32 v17, v17, 0x3a800000, v162
	v_cmp_gt_f32_e32 vcc, s7, v17
	v_mul_f32_e32 v18, 0x4b800000, v17
	s_nop 0
	v_cndmask_b32_e32 v17, v17, v18, vcc
	v_rsq_f32_e32 v17, v17
	s_nop 0
	v_mul_f32_e32 v18, 0x45800000, v17
	v_cndmask_b32_e32 v47, v17, v18, vcc
	v_mul_f32_e32 v21, v12, v47
	s_waitcnt vmcnt(9)
	v_mul_f32_e32 v21, v48, v21
	v_add_f32_e32 v29, 1.0, v52
	v_fma_f32 v16, v29, v21, v60
	v_mul_f32_e32 v21, v13, v47
	v_mul_f32_e32 v21, v49, v21
	v_add_f32_e32 v29, 1.0, v53
	v_fma_f32 v17, v29, v21, v61
	v_mul_f32_e32 v21, v14, v47
	v_mul_f32_e32 v21, v50, v21
	v_add_f32_e32 v29, 1.0, v54
	v_fma_f32 v21, v29, v21, v62
	v_mul_f32_e32 v18, v15, v47
	v_mul_f32_e32 v18, v51, v18
	v_add_f32_e32 v29, 1.0, v55
	v_fmac_f32_e32 v63, v18, v29
	s_nop 1
	v_cvt_pk_bf16_f32 v18, v16, v17
	v_lshl_add_u64 v[16:17], v[26:27], 0, v[40:41]
	s_nop 1
	v_cvt_pk_bf16_f32 v19, v21, v63
	global_store_dwordx2 v[16:17], v[18:19], off
	s_and_saveexec_b64 s[38:39], s[36:37]
	s_cbranch_execz .LBB0_1010
	v_lshl_add_u64 v[56:57], v[34:35], 0, v[160:161]
	global_store_dwordx4 v[56:57], v[12:15], off
.LBB0_1010:
	s_or_b64 exec, exec, s[38:39]
	v_mul_f32_e32 v18, v8, v47
	s_waitcnt vmcnt(7)
	v_mul_f32_e32 v64, v18, v64
	v_add_f32_e32 v18, 1.0, v68
	v_fma_f32 v64, v64, v18, v72
	v_mul_f32_e32 v18, v9, v47
	v_mul_f32_e32 v65, v18, v65
	v_add_f32_e32 v18, 1.0, v69
	v_fma_f32 v65, v65, v18, v73
	v_mul_f32_e32 v18, v10, v47
	v_mul_f32_e32 v66, v18, v66
	v_add_f32_e32 v18, 1.0, v70
	v_fma_f32 v66, v66, v18, v74
	v_mul_f32_e32 v18, v11, v47
	v_mul_f32_e32 v67, v18, v67
	v_add_f32_e32 v18, 1.0, v71
	v_fmac_f32_e32 v75, v67, v18
	s_nop 1
	v_cvt_pk_bf16_f32 v64, v64, v65
	s_nop 1
	v_cvt_pk_bf16_f32 v65, v66, v75
	global_store_dwordx2 v[16:17], v[64:65], off offset:512
	s_and_saveexec_b64 s[38:39], s[36:37]
	s_cbranch_execz .LBB0_1012
	v_lshl_add_u64 v[56:57], v[34:35], 0, v[160:161]
	global_store_dwordx4 v[56:57], v[8:11], off offset:1024
.LBB0_1012:
	s_or_b64 exec, exec, s[38:39]
	v_mul_f32_e32 v18, v4, v47
	s_waitcnt vmcnt(5)
	v_mul_f32_e32 v76, v18, v76
	v_add_f32_e32 v18, 1.0, v84
	v_fma_f32 v76, v76, v18, v80
	v_mul_f32_e32 v18, v5, v47
	v_mul_f32_e32 v77, v18, v77
	v_add_f32_e32 v18, 1.0, v85
	v_fma_f32 v77, v77, v18, v81
	v_mul_f32_e32 v18, v6, v47
	v_mul_f32_e32 v78, v18, v78
	v_add_f32_e32 v18, 1.0, v86
	v_fma_f32 v78, v78, v18, v82
	v_mul_f32_e32 v18, v7, v47
	v_mul_f32_e32 v79, v18, v79
	v_add_f32_e32 v18, 1.0, v87
	v_fmac_f32_e32 v83, v79, v18
	s_nop 1
	v_cvt_pk_bf16_f32 v76, v76, v77
	s_nop 1
	v_cvt_pk_bf16_f32 v77, v78, v83
	global_store_dwordx2 v[16:17], v[76:77], off offset:1024
	s_and_saveexec_b64 s[38:39], s[36:37]
	s_cbranch_execz .LBB0_1014
	v_lshl_add_u64 v[56:57], v[34:35], 0, v[160:161]
	global_store_dwordx4 v[56:57], v[4:7], off offset:2048
.LBB0_1014:
	s_or_b64 exec, exec, s[38:39]
	v_mul_f32_e32 v18, v0, v47
	s_waitcnt vmcnt(3)
	v_mul_f32_e32 v88, v18, v88
	v_add_f32_e32 v18, 1.0, v96
	v_fma_f32 v88, v88, v18, v92
	v_mul_f32_e32 v18, v1, v47
	v_mul_f32_e32 v89, v18, v89
	v_add_f32_e32 v18, 1.0, v97
	v_fma_f32 v89, v89, v18, v93
	v_mul_f32_e32 v18, v2, v47
	v_mul_f32_e32 v90, v18, v90
	v_add_f32_e32 v18, 1.0, v98
	v_fma_f32 v90, v90, v18, v94
	v_mul_f32_e32 v18, v3, v47
	v_mul_f32_e32 v91, v18, v91
	v_add_f32_e32 v18, 1.0, v99
	v_fmac_f32_e32 v95, v91, v18
	s_nop 1
	v_cvt_pk_bf16_f32 v88, v88, v89
	s_nop 1
	v_cvt_pk_bf16_f32 v89, v90, v95
	global_store_dwordx2 v[16:17], v[88:89], off offset:1536
	s_and_saveexec_b64 s[38:39], s[36:37]
	s_cbranch_execz .LBB0_997
	v_lshl_add_u64 v[56:57], v[34:35], 0, v[160:161]
	global_store_dwordx4 v[56:57], v[0:3], off offset:3072
	s_branch .LBB0_997
